# relax store-draining vmcnt waits in GLA summary and GLA output unit loops (loop-carried loads no longer wait on unit output stores)
# speedup vs baseline: 1.0059x; 1.0059x over previous
; __device__ __forceinline__ float bf2f(u16 h) { return __uint_as_float(((unsigned)h) << 16); }
; #define LBAR do { asm volatile("s_waitcnt lgkmcnt(0)" ::: "memory"); __builtin_amdgcn_s_barrier(); } while (0)
; __device__ __forceinline__ void gla_cumsum(const P& p, uint4 a, uint4 b, char* sm) {
;   float* bF = (float*)(sm + G_BF);
;   float* bB = (float*)(sm + G_BB);
;   int tid = opaque_tid(p);
;   {
;     int s = tid >> 3, d0 = (tid & 7) * 8;
;     const u16* pa = (const u16*)&a; const u16* pb = (const u16*)&b;
; #pragma unroll
;     for (int e = 0; e < 8; ++e) { bF[s * 65 + d0 + e] = bf2f(pa[e]); bB[s * 65 + d0 + e] = bf2f(pb[e]); }
;   }
;   LBAR;
.LBB0_222:
	s_or_b64 exec, exec, s[0:1]
	s_cmpk_lt_i32 s2, 0x1000
	s_cselect_b64 s[6:7], -1, 0
	s_cmpk_gt_i32 s2, 0xfff
	s_waitcnt lgkmcnt(0)
	s_barrier
	v_mbcnt_lo_u32_b32 v16, -1, 0
	v_mbcnt_hi_u32_b32 v16, -1, v16
	s_cbranch_scc1 .LBB0_229
	v_add_u32_e32 v0, s33, v16
	v_readlane_b32 s3, v255, 1
	v_ashrrev_i32_e32 v33, 3, v0
	s_and_b32 s0, s3, 0xffffffc0
	v_lshlrev_b32_e32 v17, 3, v0
	v_add_u32_e32 v0, s0, v33
	v_ashrrev_i32_e32 v1, 31, v0
	s_lshl_b32 s0, s2, 6
	v_and_b32_e32 v32, 56, v17
	v_lshlrev_b64 v[0:1], 8, v[0:1]
	s_and_b32 s0, s0, 0xc0
	v_or3_b32 v0, v0, s0, v32
	v_lshlrev_b64 v[0:1], 1, v[0:1]
	v_lshl_add_u64 v[8:9], s[12:13], 0, v[0:1]
	v_lshl_add_u64 v[10:11], s[14:15], 0, v[0:1]
	global_load_dwordx4 v[4:7], v[8:9], off
	global_load_dwordx4 v[0:3], v[10:11], off
	s_add_u32 s4, s34, 0x16000000
	v_bfi_b32 v8, 63, v16, s3
	s_addc_u32 s5, s35, 0
	v_ashrrev_i32_e32 v9, 31, v8
	s_ashr_i32 s3, s2, 31
	v_lshlrev_b64 v[8:9], 9, v[8:9]
	s_lshl_b32 s0, s0, 1
	s_lshl_b64 s[8:9], s[2:3], 14
	s_mov_b32 s1, 0
	v_lshl_add_u64 v[8:9], s[4:5], 0, v[8:9]
	v_and_b32_e32 v36, -8, v33
	s_add_u32 s8, s18, s8
	v_lshlrev_b32_e32 v38, 6, v33
	v_lshl_add_u64 v[8:9], v[8:9], 0, s[0:1]
	v_ashrrev_i32_e32 v37, 31, v36
	s_addc_u32 s9, s19, s9
	v_ashrrev_i32_e32 v39, 31, v38
	v_mov_b32_e32 v35, 0
	v_lshl_add_u64 v[12:13], v[36:37], 1, v[8:9]
	v_lshl_add_u64 v[8:9], v[38:39], 1, s[8:9]
	v_lshlrev_b32_e32 v34, 1, v32
	v_lshl_add_u64 v[14:15], v[8:9], 0, v[34:35]
	global_load_dwordx4 v[28:31], v[12:13], off
	global_load_dwordx4 v[8:11], v[14:15], off
	v_and_b32_e32 v12, 0xffffffc0, v17
	v_add_u32_e32 v40, 0x1000, v12
	v_ashrrev_i32_e32 v41, 31, v40
	v_lshl_add_u64 v[12:13], v[40:41], 1, s[8:9]
	v_lshl_add_u64 v[12:13], v[12:13], 0, v[34:35]
	global_load_dwordx4 v[12:15], v[12:13], off
	s_add_u32 s8, s34, 0x1f400000
	s_addc_u32 s9, s35, 0
	s_add_u32 s10, s50, 4
	v_and_b32_e32 v46, 63, v16
	s_addc_u32 s11, s51, 0
	s_lshl_b32 s20, s2, 1
	s_lshl_b32 s3, s70, 1
	s_movk_i32 s28, 0x41
	s_movk_i32 s29, 0x820
	s_movk_i32 s30, 0x104
	s_add_i32 s31, 16, 0x18800
	s_movk_i32 s40, 0x100
	s_movk_i32 s41, 0x240
	s_movk_i32 s42, 0x48
	s_movk_i32 s43, 0x90
	s_add_i32 s44, 16, 0x11200
	s_movk_i32 s45, 0x80
	s_mov_b64 s[22:23], 0x800
	v_mov_b32_e32 v47, 0x4100
	v_mov_b32_e32 v48, 0x3ffc
	v_mov_b32_e32 v49, 0xa600
	v_mov_b32_e32 v50, 0x8200
	s_mov_b32 s21, s2
	s_waitcnt vmcnt(0)
.LBB0_224:
	s_add_i32 s46, s21, s70
	s_cmpk_gt_i32 s46, 0xfff
	s_cselect_b64 s[24:25], -1, 0
	s_cmpk_lt_i32 s46, 0x1000
	s_cselect_b32 s26, s46, s21
	s_lshl_b32 s0, s26, 4
	s_andn2_b32 s0, s0, 63
	v_add_u32_e32 v16, s0, v33
	v_ashrrev_i32_e32 v17, 31, v16
	s_lshl_b32 s27, s26, 6
	v_lshlrev_b64 v[16:17], 8, v[16:17]
	s_and_b32 s27, s27, 0xc0
	v_or_b32_e32 v20, s0, v46
	v_or_b32_e32 v16, s27, v16
	v_ashrrev_i32_e32 v21, 31, v20
	s_lshl_b32 s0, s27, 1
	s_ashr_i32 s27, s26, 31
	v_lshlrev_b64 v[20:21], 9, v[20:21]
	s_lshl_b64 s[26:27], s[26:27], 14
	v_lshl_add_u64 v[20:21], s[4:5], 0, v[20:21]
	s_add_u32 s26, s18, s26
	v_lshl_add_u64 v[20:21], v[20:21], 0, s[0:1]
	s_addc_u32 s27, s19, s27
	v_or_b32_e32 v16, v16, v32
	v_lshl_add_u64 v[24:25], v[36:37], 1, v[20:21]
	v_lshl_add_u64 v[20:21], v[38:39], 1, s[26:27]
	v_lshlrev_b32_e32 v34, 1, v32
	v_lshlrev_b64 v[16:17], 1, v[16:17]
	v_lshl_add_u64 v[26:27], v[20:21], 0, v[34:35]
	v_lshl_add_u64 v[20:21], v[40:41], 1, s[26:27]
	v_lshl_add_u64 v[18:19], s[12:13], 0, v[16:17]
	v_lshl_add_u64 v[16:17], s[14:15], 0, v[16:17]
	v_lshl_add_u64 v[20:21], v[20:21], 0, v[34:35]
	s_waitcnt vmcnt(12)
	v_and_b32_e32 v44, 0xffff0000, v4
	v_lshlrev_b32_e32 v45, 16, v5
	v_and_b32_e32 v52, 0xffff0000, v5
	v_and_b32_e32 v53, 0xffff0000, v6
	v_lshlrev_b32_e32 v54, 16, v7
	v_and_b32_e32 v55, 0xffff0000, v7
	s_waitcnt vmcnt(11)
	v_and_b32_e32 v56, 0xffff0000, v0
	v_lshlrev_b32_e32 v57, 16, v1
	v_and_b32_e32 v58, 0xffff0000, v1
	v_and_b32_e32 v59, 0xffff0000, v2
	v_lshlrev_b32_e32 v60, 16, v3
	v_and_b32_e32 v61, 0xffff0000, v3
	v_lshlrev_b32_e32 v62, 16, v4
	v_lshlrev_b32_e32 v63, 16, v0
	v_lshlrev_b32_e32 v64, 16, v6
	v_lshlrev_b32_e32 v65, 16, v2
	global_load_dwordx4 v[4:7], v[18:19], off
	global_load_dwordx4 v[0:3], v[16:17], off
	s_nop 0
	global_load_dwordx4 v[20:23], v[20:21], off
	s_nop 0
	global_load_dwordx4 v[16:19], v[24:25], off
	s_nop 0
	global_load_dwordx4 v[24:27], v[26:27], off
	v_mbcnt_lo_u32_b32 v51, -1, 0
	v_mbcnt_hi_u32_b32 v51, -1, v51
	v_mbcnt_lo_u32_b32 v66, -1, 0
	v_mbcnt_hi_u32_b32 v66, -1, v66
	s_waitcnt vmcnt(13)
	v_lshlrev_b32_e32 v74, 16, v28
	v_add_u32_e32 v67, s33, v66
	v_lshlrev_b32_e32 v34, 3, v66
	v_ashrrev_i32_e32 v42, 3, v67
	v_and_b32_e32 v34, 56, v34
	v_mad_u64_u32 v[42:43], s[26:27], v42, s28, v[34:35]
	v_lshl_add_u32 v34, v42, 2, 16
	v_add_u32_e32 v42, 0x4104, v34
	ds_write2_b32 v34, v44, v45 offset0:1 offset1:2
	ds_write2_b32 v42, v56, v57 offset1:1
	v_add_u32_e32 v42, 0x410c, v34
	ds_write2_b32 v34, v52, v64 offset0:3 offset1:4
	ds_write2_b32 v42, v58, v65 offset1:1
	v_add_u32_e32 v42, 0x4114, v34
	ds_write2_b32 v34, v53, v54 offset0:5 offset1:6
	ds_write2_b32 v42, v59, v60 offset1:1
	ds_write2_b32 v34, v62, v55 offset1:7
	v_add_u32_e32 v34, 0x4000, v34
	ds_write2_b32 v34, v63, v61 offset0:64 offset1:71
	v_lshlrev_b32_e32 v34, 2, v66
	v_and_b32_e32 v57, 0xfc, v34
	v_ashrrev_i32_e32 v56, 6, v67
	v_add_u32_e32 v34, 16, v57
	v_mad_u64_u32 v[44:45], s[26:27], v56, s29, v[34:35]
	v_lshl_or_b32 v42, v56, 3, 1
	s_waitcnt lgkmcnt(0)
	s_barrier
; #define LBAR do { asm volatile("s_waitcnt lgkmcnt(0)" ::: "memory"); __builtin_amdgcn_s_barrier(); } while (0)
; __device__ __forceinline__ void gla_cumsum(const P& p, uint4 a, uint4 b, char* sm) {
;     ...
;   {
;     float* segF = (float*)(sm + G_SEG);
;     float* segB = segF + 8 * 64;
;     int dk = tid & 63, seg = tid >> 6;
;     float a = 0.f, c = 0.f;
; #pragma unroll
;     for (int i = 0; i < 8; ++i) { a += bF[(seg * 8 + i) * 65 + dk]; bF[(seg * 8 + i) * 65 + dk] = a; }
; #pragma unroll
;     for (int i = 7; i >= 0; --i) { c += bB[(seg * 8 + i) * 65 + dk]; bB[(seg * 8 + i) * 65 + dk] = c; }
;     segF[seg * 64 + dk] = a; segB[seg * 64 + dk] = c;
;     LBAR;
;     float offF = 0.f, offB = 0.f;
; #pragma unroll
;     for (int s2 = 0; s2 < 8; ++s2) {
;       float f = segF[s2 * 64 + dk], g = segB[s2 * 64 + dk];
;       offF += (s2 < seg) ? f : 0.f;
;       offB += (s2 > seg) ? g : 0.f;
;     }
; #pragma unroll
;     for (int i = 0; i < 8; ++i) { bF[(seg * 8 + i) * 65 + dk] += offF; bB[(seg * 8 + i) * 65 + dk] += offB; }
;   }
;   LBAR;
	ds_read_b32 v45, v44
	v_mad_u64_u32 v[42:43], s[26:27], v42, s30, v[34:35]
	ds_read2_b32 v[52:53], v42 offset1:65
	ds_read2_b32 v[54:55], v42 offset0:130 offset1:195
	s_waitcnt lgkmcnt(2)
	v_add_f32_e32 v34, 0, v45
	ds_write_b32 v44, v34
	v_add_u32_e32 v59, 0x4400, v42
	s_waitcnt lgkmcnt(2)
	v_add_f32_e32 v34, v34, v52
	v_add_f32_e32 v43, v34, v53
	ds_write2_b32 v42, v34, v43 offset1:65
	s_waitcnt lgkmcnt(2)
	v_add_f32_e32 v34, v43, v54
	v_add_f32_e32 v43, v34, v55
	ds_write2_b32 v42, v34, v43 offset0:130 offset1:195
	v_add_u32_e32 v34, 0x400, v42
	ds_read2_b32 v[52:53], v34 offset0:4 offset1:69
	v_and_b32_e32 v75, 0xffff0000, v28
	v_add_u32_e32 v61, 0x4200, v42
	v_add_u32_e32 v62, 0x4000, v42
	v_cmp_lt_i32_e32 vcc, 0, v56
	s_waitcnt lgkmcnt(0)
	v_add_f32_e32 v43, v43, v52
	v_add_f32_e32 v45, v43, v53
	ds_write2_b32 v34, v43, v45 offset0:4 offset1:69
	ds_read_b32 v43, v42 offset:1560
	ds_read_b32 v52, v42 offset:18200
	v_or_b32_e32 v65, 0x500, v57
	v_add_u32_e32 v66, s84, v65
	v_add_u32_e32 v65, s31, v65
	s_waitcnt lgkmcnt(1)
	v_add_f32_e32 v58, v45, v43
	s_waitcnt lgkmcnt(0)
	v_add_f32_e32 v45, 0, v52
	ds_write_b32 v42, v58 offset:1560
	ds_write_b32 v42, v45 offset:18200
	ds_read2_b32 v[52:53], v59 offset0:68 offset1:133
	v_add_u32_e32 v43, s33, v51
	v_lshlrev_b32_e32 v77, 16, v31
	v_and_b32_e32 v78, 0xffff0000, v31
	v_lshlrev_b32_e32 v76, 16, v29
	s_waitcnt lgkmcnt(0)
	v_add_f32_e32 v28, v45, v53
	v_add_f32_e32 v60, v28, v52
	ds_write2_b32 v59, v60, v28 offset0:68 offset1:133
	ds_read2_b32 v[52:53], v61 offset0:66 offset1:131
	ds_read2_b32 v[54:55], v62 offset0:64 offset1:129
	v_ashrrev_i32_e32 v45, 6, v43
	v_and_b32_e32 v28, 63, v51
	v_mul_lo_u32 v79, v45, s41
	s_waitcnt lgkmcnt(1)
	v_add_f32_e32 v53, v60, v53
	ds_read_b32 v60, v44 offset:16640
	v_add_f32_e32 v52, v53, v52
	ds_write2_b32 v61, v52, v53 offset0:66 offset1:131
	s_waitcnt lgkmcnt(2)
	v_add_f32_e32 v52, v52, v55
	v_add_f32_e32 v53, v52, v54
	ds_write2_b32 v62, v53, v52 offset0:64 offset1:129
	s_waitcnt lgkmcnt(2)
	v_add_f32_e32 v52, v53, v60
	v_lshlrev_b32_e32 v53, 2, v67
	v_add_u32_e32 v54, s84, v53
	ds_write_b32 v44, v52 offset:16640
	ds_write_b32 v54, v58
	v_add_u32_e32 v53, s31, v53
	v_or_b32_e32 v54, 0x100, v57
	v_or_b32_e32 v58, 0x200, v57
	ds_write_b32 v53, v52
	v_add_u32_e32 v52, s84, v57
	v_add_u32_e32 v53, s31, v57
	v_add_u32_e32 v55, s84, v54
	v_add_u32_e32 v54, s31, v54
	v_add_u32_e32 v60, s84, v58
	v_add_u32_e32 v58, s31, v58
	s_waitcnt lgkmcnt(0)
	s_barrier
	ds_read_b32 v52, v52
	ds_read_b32 v53, v53
	ds_read_b32 v55, v55
	ds_read_b32 v54, v54
	ds_read_b32 v60, v60
	ds_read_b32 v58, v58
	ds_read_b32 v63, v42 offset:1560
	ds_read_b32 v64, v42 offset:18200
	s_waitcnt lgkmcnt(7)
	v_add_f32_e32 v52, 0, v52
	v_cndmask_b32_e32 v52, 0, v52, vcc
	s_waitcnt lgkmcnt(6)
	v_add_f32_e32 v53, 0, v53
	v_cmp_gt_i32_e32 vcc, 0, v56
	v_or_b32_e32 v67, 0x600, v57
	v_add_u32_e32 v68, s84, v67
	v_cndmask_b32_e32 v53, 0, v53, vcc
	v_cmp_lt_i32_e32 vcc, 1, v56
	v_add_u32_e32 v67, s31, v67
	v_and_b32_e32 v29, 0xffff0000, v29
	s_waitcnt lgkmcnt(5)
	v_cndmask_b32_e32 v55, 0, v55, vcc
	v_cmp_gt_i32_e32 vcc, 1, v56
	v_add_f32_e32 v52, v52, v55
	s_waitcnt lgkmcnt(4)
	v_cndmask_b32_e32 v54, 0, v54, vcc
	v_cmp_lt_i32_e32 vcc, 2, v56
	v_add_f32_e32 v53, v53, v54
	s_waitcnt lgkmcnt(3)
	v_cndmask_b32_e32 v54, 0, v60, vcc
	v_cmp_gt_i32_e32 vcc, 2, v56
	v_add_f32_e32 v52, v52, v54
	s_waitcnt lgkmcnt(2)
	v_cndmask_b32_e32 v54, 0, v58, vcc
	v_add_f32_e32 v53, v53, v54
	v_or_b32_e32 v54, 0x300, v57
	v_or_b32_e32 v58, 0x400, v57
	v_add_u32_e32 v55, s84, v54
	v_add_u32_e32 v54, s31, v54
	v_add_u32_e32 v60, s84, v58
	v_add_u32_e32 v58, s31, v58
	ds_read_b32 v55, v55
	ds_read_b32 v54, v54
	ds_read_b32 v60, v60
	ds_read_b32 v58, v58
	ds_read_b32 v66, v66
	ds_read_b32 v65, v65
	ds_read_b32 v68, v68
	ds_read_b32 v67, v67
	v_cmp_lt_i32_e32 vcc, 3, v56
	s_waitcnt lgkmcnt(7)
	s_nop 0
	v_cndmask_b32_e32 v55, 0, v55, vcc
	v_cmp_gt_i32_e32 vcc, 3, v56
	v_add_f32_e32 v52, v52, v55
	v_or_b32_e32 v55, 0x700, v57
	s_waitcnt lgkmcnt(6)
	v_cndmask_b32_e32 v54, 0, v54, vcc
	v_cmp_lt_i32_e32 vcc, 4, v56
	v_add_f32_e32 v53, v53, v54
	v_add_u32_e32 v57, s84, v55
	s_waitcnt lgkmcnt(5)
	v_cndmask_b32_e32 v54, 0, v60, vcc
	v_cmp_gt_i32_e32 vcc, 4, v56
	v_add_f32_e32 v52, v52, v54
	ds_read_b32 v57, v57
	s_waitcnt lgkmcnt(5)
	v_cndmask_b32_e32 v54, 0, v58, vcc
	v_cmp_lt_i32_e32 vcc, 5, v56
	v_add_f32_e32 v53, v53, v54
	s_waitcnt lgkmcnt(4)
	v_cndmask_b32_e32 v54, 0, v66, vcc
	v_cmp_gt_i32_e32 vcc, 5, v56
	v_add_f32_e32 v52, v52, v54
	s_waitcnt lgkmcnt(3)
	v_cndmask_b32_e32 v54, 0, v65, vcc
	v_cmp_lt_i32_e32 vcc, 6, v56
	v_add_f32_e32 v53, v53, v54
	s_waitcnt lgkmcnt(2)
	v_cndmask_b32_e32 v54, 0, v68, vcc
	v_cmp_gt_i32_e32 vcc, 6, v56
	v_add_f32_e32 v52, v52, v54
	s_waitcnt lgkmcnt(1)
	v_cndmask_b32_e32 v54, 0, v67, vcc
	v_add_f32_e32 v54, v53, v54
	v_add_u32_e32 v53, s31, v55
	ds_read_b32 v55, v53
	v_cmp_lt_i32_e32 vcc, 7, v56
	s_waitcnt lgkmcnt(1)
	s_nop 0
	v_cndmask_b32_e32 v53, 0, v57, vcc
	v_add_f32_e32 v58, v52, v53
	ds_read2st64_b32 v[52:53], v44 offset1:65
	v_cmp_gt_i32_e32 vcc, 7, v56
	s_waitcnt lgkmcnt(0)
	v_add_f32_e32 v52, v58, v52
	v_cndmask_b32_e32 v55, 0, v55, vcc
	v_add_f32_e32 v60, v54, v55
	ds_read2_b32 v[54:55], v42 offset1:65
	ds_read2_b32 v[56:57], v62 offset0:64 offset1:129
	v_add_f32_e32 v53, v60, v53
	ds_write2st64_b32 v44, v52, v53 offset1:65
	v_cmp_gt_i32_e32 vcc, s45, v43
	s_waitcnt lgkmcnt(2)
	v_add_f32_e32 v44, v58, v54
	v_add_f32_e32 v65, v58, v55
	ds_read2_b32 v[52:53], v42 offset0:130 offset1:195
	ds_read2_b32 v[54:55], v61 offset0:66 offset1:131
	s_waitcnt lgkmcnt(3)
	v_add_f32_e32 v56, v60, v56
	ds_write2_b32 v42, v44, v65 offset1:65
	v_add_f32_e32 v44, v60, v57
	ds_write2_b32 v62, v56, v44 offset0:64 offset1:129
	s_waitcnt lgkmcnt(3)
	v_add_f32_e32 v44, v58, v52
	v_add_f32_e32 v62, v58, v53
	ds_read2_b32 v[52:53], v34 offset0:4 offset1:69
	ds_read2_b32 v[56:57], v59 offset0:68 offset1:133
	s_waitcnt lgkmcnt(4)
	v_add_f32_e32 v54, v60, v54
	ds_write2_b32 v42, v44, v62 offset0:130 offset1:195
	v_add_f32_e32 v44, v60, v55
	ds_write2_b32 v61, v54, v44 offset0:66 offset1:131
	s_waitcnt lgkmcnt(3)
	v_add_f32_e32 v44, v58, v52
	v_add_f32_e32 v53, v58, v53
	s_waitcnt lgkmcnt(2)
	v_add_f32_e32 v52, v60, v56
	ds_write2_b32 v34, v44, v53 offset0:4 offset1:69
	v_add_f32_e32 v34, v60, v57
	ds_write2_b32 v59, v52, v34 offset0:68 offset1:133
	v_add_f32_e32 v34, v58, v63
	ds_write_b32 v42, v34 offset:1560
	v_add_f32_e32 v34, v60, v64
	ds_write_b32 v42, v34 offset:18200
	v_lshl_add_u32 v42, v45, 5, 16
	v_mul_u32_u24_e32 v34, 0x41, v28
	v_add_u32_e32 v44, 0x3ffc, v42
	s_waitcnt lgkmcnt(0)
	s_barrier
; __device__ __forceinline__ float bf2f(u16 h) { return __uint_as_float(((unsigned)h) << 16); }
; __device__ __forceinline__ void gla_summ_unit(const P& p, int unit, const SummRaw& raw) {
;     ...
;   {
;     int s = tid & 63, dg = tid >> 6;
;     const u16* pk = (const u16*)&raw.k;
; #pragma unroll
;     for (int e = 0; e < 8; ++e) {
;       int dk = dg * 8 + e;
;       float k = bf2f(pk[e]);
;       kdfT[dk * LP + s] = f2bf(k * __expf(bF[63 * 65 + dk] - bF[s * 65 + dk]));
;       kdbT[dk * LP + s] = f2bf(k * __expf(bB[0 * 65 + dk] - bB[s * 65 + dk]));
;     }
;     *(uint4*)(vT + (tid >> 3) * LP + (tid & 7) * 8) = raw.v0;
;     *(uint4*)(vT + ((tid + 512) >> 3) * LP + (tid & 7) * 8) = raw.v1;
;     if (tid < 128) {
;       int dir = tid >> 6, dk = tid & 63;
;       float* dec = (float*)(p.ws + OFF_DEC);
;       dec[(size_t)(unit * 2 + dir) * 64 + dk] = __expf(dir == 0 ? bF[63 * 65 + dk] : bB[dk]);
;     }
;   }
	v_lshl_add_u32 v34, v34, 2, v42
	ds_read2_b32 v[60:61], v44 offset1:1
	ds_read2_b32 v[62:63], v34 offset1:1
	v_lshlrev_b32_e32 v44, 16, v30
	ds_read2_b32 v[64:65], v34 offset0:2 offset1:3
	ds_read2_b32 v[66:67], v34 offset0:4 offset1:5
	v_add_u32_e32 v68, 0x4004, v42
	v_add_u32_e32 v70, 0x4108, v34
	s_waitcnt lgkmcnt(2)
	v_sub_f32_e32 v52, v60, v62
	v_mul_f32_e32 v52, 0x3fb8aa3b, v52
	v_exp_f32_e32 v52, v52
	v_and_b32_e32 v62, 0xffff0000, v30
	v_mul_f32_e32 v30, v52, v74
	v_cvt_pk_bf16_f32 v60, v30, s0
	v_add_u32_e32 v30, 0x4100, v34
	ds_read2_b32 v[30:31], v30 offset1:1
	ds_read_b128 v[52:55], v42 offset:16640
	ds_read_b128 v[56:59], v42 offset:16656
	ds_read2_b32 v[68:69], v68 offset1:1
	ds_read2_b32 v[70:71], v70 offset1:1
	ds_read2_b32 v[72:73], v34 offset0:6 offset1:7
	s_waitcnt lgkmcnt(4)
	v_sub_f32_e32 v30, v52, v30
	v_mul_f32_e32 v30, 0x3fb8aa3b, v30
	v_exp_f32_e32 v30, v30
	v_sub_f32_e32 v31, v53, v31
	v_mul_f32_e32 v31, 0x3fb8aa3b, v31
	v_or_b32_e32 v52, v79, v28
	v_mul_f32_e32 v30, v30, v74
	v_exp_f32_e32 v53, v31
	v_lshl_add_u32 v52, v52, 1, 16
	v_cvt_pk_bf16_f32 v30, v30, s0
	ds_write_b16 v52, v30 offset:42496
	v_lshl_or_b32 v30, v45, 3, 1
	v_mad_u64_u32 v[30:31], s[26:27], v30, s42, v[28:29]
	ds_write_b16 v52, v60 offset:33280
	v_sub_f32_e32 v60, v61, v63
	v_lshl_add_u32 v63, v30, 1, 16
	v_mul_f32_e32 v30, v53, v75
	v_cvt_pk_bf16_f32 v30, v30, s0
	ds_write_b16 v63, v30 offset:42496
	s_waitcnt lgkmcnt(5)
	v_sub_f32_e32 v30, v68, v64
	v_mul_f32_e32 v30, 0x3fb8aa3b, v30
	v_exp_f32_e32 v30, v30
	s_waitcnt lgkmcnt(4)
	v_sub_f32_e32 v31, v54, v70
	v_mul_f32_e32 v31, 0x3fb8aa3b, v31
	v_exp_f32_e32 v31, v31
	v_mul_f32_e32 v30, v30, v76
	v_cvt_pk_bf16_f32 v30, v30, s0
	ds_write_b16 v63, v30 offset:33424
	v_mul_f32_e32 v30, v31, v76
	v_cvt_pk_bf16_f32 v30, v30, s0
	ds_write_b16 v63, v30 offset:42640
	v_sub_f32_e32 v30, v69, v65
	v_sub_f32_e32 v31, v55, v71
	v_mul_f32_e32 v30, 0x3fb8aa3b, v30
	v_mul_f32_e32 v31, 0x3fb8aa3b, v31
	v_exp_f32_e32 v30, v30
	v_exp_f32_e32 v31, v31
	v_mul_f32_e32 v60, 0x3fb8aa3b, v60
	v_exp_f32_e32 v60, v60
	v_mul_f32_e32 v30, v30, v29
	v_mul_f32_e32 v29, v31, v29
	v_cvt_pk_bf16_f32 v29, v29, s0
	v_cvt_pk_bf16_f32 v30, v30, s0
	ds_write_b16 v63, v29 offset:42784
	v_add_u32_e32 v29, 0x400c, v42
	ds_write_b16 v63, v30 offset:33568
	ds_read2_b32 v[30:31], v29 offset1:1
	v_mul_f32_e32 v52, v60, v75
	v_cvt_pk_bf16_f32 v52, v52, s0
	ds_write_b16 v63, v52 offset:33280
	v_add_u32_e32 v29, 0x4110, v34
	v_add_u32_e32 v42, 0x4014, v42
	v_add_u32_e32 v34, 0x4118, v34
	ds_read2_b32 v[52:53], v29 offset1:1
	ds_read2_b32 v[54:55], v42 offset1:1
	ds_read2_b32 v[60:61], v34 offset1:1
	s_waitcnt lgkmcnt(4)
	v_sub_f32_e32 v29, v30, v66
	v_mul_f32_e32 v29, 0x3fb8aa3b, v29
	v_exp_f32_e32 v29, v29
	s_waitcnt lgkmcnt(2)
	v_sub_f32_e32 v30, v56, v52
	v_mul_f32_e32 v30, 0x3fb8aa3b, v30
	v_exp_f32_e32 v30, v30
	v_mul_f32_e32 v29, v29, v44
	v_cvt_pk_bf16_f32 v29, v29, s0
	ds_write_b16 v63, v29 offset:33712
	v_mul_f32_e32 v29, v30, v44
	v_cvt_pk_bf16_f32 v29, v29, s0
	ds_write_b16 v63, v29 offset:42928
	v_sub_f32_e32 v29, v31, v67
	v_mul_f32_e32 v29, 0x3fb8aa3b, v29
	v_exp_f32_e32 v29, v29
	v_sub_f32_e32 v30, v57, v53
	v_mul_f32_e32 v30, 0x3fb8aa3b, v30
	v_exp_f32_e32 v30, v30
	v_mul_f32_e32 v29, v29, v62
	v_cvt_pk_bf16_f32 v29, v29, s0
	ds_write_b16 v63, v29 offset:33856
	v_mul_f32_e32 v29, v30, v62
	v_cvt_pk_bf16_f32 v29, v29, s0
	ds_write_b16 v63, v29 offset:43072
	s_waitcnt lgkmcnt(5)
	v_sub_f32_e32 v29, v54, v72
	v_mul_f32_e32 v29, 0x3fb8aa3b, v29
	v_exp_f32_e32 v29, v29
	s_waitcnt lgkmcnt(4)
	v_sub_f32_e32 v30, v58, v60
	v_mul_f32_e32 v30, 0x3fb8aa3b, v30
	v_exp_f32_e32 v30, v30
	v_mul_f32_e32 v29, v29, v77
	v_cvt_pk_bf16_f32 v29, v29, s0
	ds_write_b16 v63, v29 offset:34000
	v_mul_f32_e32 v29, v30, v77
	v_cvt_pk_bf16_f32 v29, v29, s0
	ds_write_b16 v63, v29 offset:43216
	v_sub_f32_e32 v29, v55, v73
	v_mul_f32_e32 v29, 0x3fb8aa3b, v29
	v_exp_f32_e32 v29, v29
	v_sub_f32_e32 v30, v59, v61
	v_mul_f32_e32 v30, 0x3fb8aa3b, v30
	v_exp_f32_e32 v30, v30
	v_mul_f32_e32 v29, v29, v78
	v_cvt_pk_bf16_f32 v29, v29, s0
	ds_write_b16 v63, v29 offset:34144
	v_mul_f32_e32 v29, v30, v78
	v_cvt_pk_bf16_f32 v29, v29, s0
	ds_write_b16 v63, v29 offset:43360
	v_lshrrev_b32_e32 v29, 3, v43
	v_lshlrev_b32_e32 v30, 4, v51
	v_mul_lo_u32 v29, v29, s43
	v_and_b32_e32 v30, 0x70, v30
	v_add3_u32 v29, s44, v29, v30
	s_waitcnt vmcnt(13)
	ds_write_b128 v29, v[8:11]
	v_add_u32_e32 v8, 0x200, v43
	v_lshrrev_b32_e32 v8, 3, v8
	v_mul_lo_u32 v8, v8, s43
	v_add3_u32 v8, s44, v8, v30
	s_waitcnt vmcnt(13)
	ds_write_b128 v8, v[12:15]
	s_and_saveexec_b64 s[26:27], vcc
	s_cbranch_execz .LBB0_226
	v_cmp_gt_u32_e32 vcc, 64, v43
	v_lshlrev_b32_e32 v34, 2, v28
	s_nop 0
	v_cndmask_b32_e32 v8, v47, v48, vcc
	v_add3_u32 v8, 16, v34, v8
	ds_read_b32 v9, v8
	v_lshl_add_u32 v8, s21, 1, v45
	s_waitcnt lgkmcnt(0)
	v_mul_f32_e32 v9, 0x3fb8aa3b, v9
	v_exp_f32_e32 v10, v9
	v_ashrrev_i32_e32 v9, 31, v8
	v_lshlrev_b64 v[8:9], 8, v[8:9]
	v_lshl_add_u64 v[8:9], s[8:9], 0, v[8:9]
	v_lshl_add_u64 v[8:9], v[8:9], 0, v[34:35]
	global_store_dword v[8:9], v10, off

; #define LBAR do { asm volatile("s_waitcnt lgkmcnt(0)" ::: "memory"); __builtin_amdgcn_s_barrier(); } while (0)
; __device__ __forceinline__ void gla_summ_unit(const P& p, int unit, const SummRaw& raw) {
;     ...
; #pragma unroll 1
;   for (int tI = 0; tI < 8; ++tI) {
;     int tile = wid * 8 + tI;
;     int dir = tile >> 5, dkt = (tile >> 3) & 3, dvt = tile & 7;
;     const u16* Asrc = (dir ? kdbT : kdfT) + (dkt * 16 + fr) * LP + fq * 8;
;     const u16* Bsrc = vT + (dvt * 16 + fr) * LP + fq * 8;
;     f32x4 d = {0.f, 0.f, 0.f, 0.f};
; #pragma unroll
;     for (int ks = 0; ks < 2; ++ks) {
;       bf16x8 a = *(const bf16x8*)(Asrc + ks * 32);
;       bf16x8 b = *(const bf16x8*)(Bsrc + ks * 32);
;       d = __builtin_amdgcn_mfma_f32_16x16x32_bf16(a, b, d, 0, 0, 0);
;     }
;     uint2 w; w.x = pack2(d[0], d[1]); w.y = pack2(d[2], d[3]);
;     *(uint2*)(kvout + (size_t)(unit * 2 + dir) * 8192 + (dvt * 16 + fr) * 64 + dkt * 16 + fq * 4) = w;
;   }
;   LBAR;
; }
; __device__ void phase_gla_summ(const P& p) {
;   int tid = opaque_tid(p);
;   int u = blockIdx.x;
;   if (u >= 4096) return;
;   SummRaw cur = gla_summ_load(p, u, tid);
;   for (; u < 4096; u += gridDim.x) {
;     int un = u + gridDim.x;
;     SummRaw nxt = gla_summ_load(p, un < 4096 ? un : u, tid);
;     gla_summ_unit(p, u, cur);
;     cur = nxt;
.LBB0_227:
	v_add_u32_e32 v31, s0, v30
	v_add_u32_e32 v34, 0x11200, v31
	s_nop 0
	ds_read_b128 v[42:45], v34
	v_add_u32_e32 v31, 0x11240, v31
	ds_read_b128 v[52:55], v31
	s_addk_i32 s0, 0x900
	s_cmpk_lg_i32 s0, 0x4800
	s_waitcnt lgkmcnt(1)
	v_mfma_f32_16x16x32_bf16 v[42:45], v[8:11], v[42:45], 0
	s_waitcnt lgkmcnt(0)
	v_mfma_f32_16x16x32_bf16 v[42:45], v[12:15], v[52:55], v[42:45]
	s_nop 7
	v_cvt_pk_bf16_f32 v42, v42, v43
	v_cvt_pk_bf16_f32 v43, v44, v45
	global_store_dwordx2 v[28:29], v[42:43], off offset:-4
	v_lshl_add_u64 v[28:29], v[28:29], 0, s[22:23]
	s_cbranch_scc1 .LBB0_227
	s_waitcnt lgkmcnt(0)
	s_add_i32 s20, s20, s3
	s_andn2_b64 vcc, exec, s[24:25]
	s_mov_b32 s21, s46
	s_waitcnt vmcnt(10)
	v_mov_b64_e32 v[12:13], v[20:21]
	v_mov_b64_e32 v[14:15], v[22:23]
	s_waitcnt vmcnt(8)
	v_mov_b64_e32 v[8:9], v[24:25]
	v_mov_b64_e32 v[10:11], v[26:27]
	v_mov_b64_e32 v[28:29], v[16:17]
	v_mov_b64_e32 v[30:31], v[18:19]
	s_barrier
	s_cbranch_vccnz .LBB0_224

; __device__ void phase_gla_out(const P& p) {
;   int tid = opaque_tid(p);
;   int u = blockIdx.x;
;   if (u >= 4096) return;
;   OutRaw cur = gla_out_load(p, u, tid);
.LBB0_382:
	s_or_b64 exec, exec, s[0:1]
	s_andn2_b64 vcc, exec, s[6:7]
	s_waitcnt lgkmcnt(0)
	s_barrier
	v_mbcnt_lo_u32_b32 v0, -1, 0
	v_mbcnt_hi_u32_b32 v0, -1, v0
	s_cbranch_vccnz .LBB0_391
	v_add_u32_e32 v0, s33, v0
	v_readlane_b32 s0, v255, 1
	s_waitcnt vmcnt(24)
	v_ashrrev_i32_e32 v97, 3, v0
	s_andn2_b32 s0, s0, 63
	v_lshlrev_b32_e32 v20, 3, v0
	v_add_u32_e32 v0, s0, v97
	s_lshl_b32 s0, s2, 6
	s_and_b32 s0, s0, 0xc0
	s_add_u32 s10, s34, 0x14000000
	s_addc_u32 s11, s35, 0
	v_ashrrev_i32_e32 v1, 31, v0
	s_add_u32 s20, s34, 0x16000000
	v_and_b32_e32 v96, 56, v20
	v_lshlrev_b64 v[0:1], 8, v[0:1]
	s_addc_u32 s21, s35, 0
	s_ashr_i32 s3, s2, 31
	v_or3_b32 v0, v0, s0, v96
	s_lshl_b64 s[0:1], s[2:3], 14
	v_lshlrev_b64 v[8:9], 1, v[0:1]
	s_add_u32 s0, s18, s0
	v_lshlrev_b32_e32 v100, 6, v97
	v_lshl_add_u64 v[10:11], s[12:13], 0, v[8:9]
	v_lshl_add_u64 v[12:13], s[14:15], 0, v[8:9]
	v_lshl_add_u64 v[16:17], s[10:11], 0, v[8:9]
	s_addc_u32 s1, s19, s1
	v_ashrrev_i32_e32 v101, 31, v100
	v_mov_b32_e32 v99, 0
	global_load_dwordx4 v[0:3], v[10:11], off
	global_load_dwordx4 v[4:7], v[12:13], off
	v_lshl_add_u64 v[18:19], s[20:21], 0, v[8:9]
	global_load_dwordx4 v[12:15], v[16:17], off
	global_load_dwordx4 v[8:11], v[18:19], off
	v_lshl_add_u64 v[16:17], v[100:101], 1, s[0:1]
	v_lshlrev_b32_e32 v98, 1, v96
	v_lshl_add_u64 v[24:25], v[16:17], 0, v[98:99]
	v_and_b32_e32 v16, 0xffffffc0, v20
	v_add_u32_e32 v102, 0x1000, v16
	v_ashrrev_i32_e32 v103, 31, v102
	v_lshl_add_u64 v[16:17], v[102:103], 1, s[0:1]
	v_lshl_add_u64 v[26:27], v[16:17], 0, v[98:99]
	global_load_dwordx4 v[20:23], v[24:25], off
	global_load_dwordx4 v[16:19], v[26:27], off
	s_mov_b64 s[22:23], 0x4000
	s_movk_i32 s3, 0x41
	s_movk_i32 s25, 0x820
	s_movk_i32 s27, 0x104
	s_add_i32 s42, 16, 0x18800
	s_movk_i32 s43, 0x200
	s_movk_i32 s44, 0x90
	s_add_i32 s45, 16, 0x11200
	s_movk_i32 s46, 0x48
	s_add_i32 s47, 16, 0x15a00
	s_add_i32 s56, 16, 0x17e00
	s_brev_b32 s24, 60
	s_mov_b32 s26, 0x358637bd
	s_mov_b32 s57, 0x800000
	s_waitcnt vmcnt(0)
	v_mov_b64_e32 v[42:43], v[22:23]
	s_branch .LBB0_385

; __device__ __forceinline__ void gla_out_unit(const P& p, int unit, const OutRaw& raw) {
;   extern __shared__ __attribute__((aligned(16))) u16 shm[];
;   char* sm = (char*)shm;
;   int chunk = unit >> 2, h = unit & 3;
;   int tid = opaque_tid(p), lane = tid & 63, wid = tid >> 6;
;   bf16x8 sB[4][2][2];
;   uint2 rav[4];
;   {
;     int fr = lane & 15, fq = lane >> 4, tt = wid >> 1, dvh = wid & 1;
;     const u16* Sst = (const u16*)((const char*)p.out + OUT_KV) + (size_t)(unit * 2) * 8192;
;     const u16* ra = (const u16*)(p.ws + OFF_RA);
; #pragma unroll
;     for (int i = 0; i < 4; ++i) {
;       int dvt = dvh * 4 + i;
; #pragma unroll
;       for (int ks = 0; ks < 2; ++ks) {
;         sB[i][ks][0] = *(const bf16x8*)(Sst + (dvt * 16 + fr) * 64 + ks * 32 + fq * 8);
;         sB[i][ks][1] = *(const bf16x8*)(Sst + 8192 + (dvt * 16 + fr) * 64 + ks * 32 + fq * 8);
;       }
;       rav[i] = *(const uint2*)(ra + ((size_t)unit * 128 + dvt * 16 + fr) * 64 + tt * 16 + fq * 4);
;     }
;   }
;   gla_cumsum(p, raw.laf, raw.lab, sm);
.LBB0_385:
	s_mov_b32 s30, s2
	s_add_i32 s2, s2, s70
	s_cmpk_gt_i32 s2, 0xfff
	s_cselect_b64 s[28:29], -1, 0
	s_cmpk_lt_i32 s2, 0x1000
	s_cselect_b32 s0, s2, s30
	s_lshl_b32 s1, s0, 4
	s_andn2_b32 s1, s1, 63
	s_waitcnt vmcnt(8)
	v_mov_b64_e32 v[32:33], v[16:17]
	v_add_u32_e32 v16, s1, v97
	v_ashrrev_i32_e32 v17, 31, v16
	s_lshl_b32 s1, s0, 6
	v_lshlrev_b64 v[16:17], 8, v[16:17]
	s_and_b32 s1, s1, 0xc0
	v_or_b32_e32 v16, s1, v16
	s_ashr_i32 s1, s0, 31
	s_lshl_b64 s[0:1], s[0:1], 14
	v_or_b32_e32 v16, v16, v96
	s_add_u32 s0, s18, s0
	v_lshlrev_b64 v[16:17], 1, v[16:17]
	s_addc_u32 s1, s19, s1
	v_mov_b64_e32 v[40:41], v[20:21]
	v_mov_b64_e32 v[34:35], v[18:19]
	v_lshl_add_u64 v[18:19], s[12:13], 0, v[16:17]
	v_lshl_add_u64 v[20:21], s[14:15], 0, v[16:17]
	v_lshl_add_u64 v[22:23], s[10:11], 0, v[16:17]
	v_lshl_add_u64 v[16:17], s[20:21], 0, v[16:17]
	v_lshl_add_u64 v[24:25], v[100:101], 1, s[0:1]
	v_lshlrev_b32_e32 v98, 1, v96
	v_lshl_add_u64 v[26:27], v[102:103], 1, s[0:1]
	s_lshl_b32 s0, s30, 1
	v_lshl_add_u64 v[24:25], v[24:25], 0, v[98:99]
	v_lshl_add_u64 v[26:27], v[26:27], 0, v[98:99]
	s_ashr_i32 s1, s0, 31
	v_and_b32_e32 v134, 0xffff0000, v0
	v_lshlrev_b32_e32 v135, 16, v1
	v_and_b32_e32 v142, 0xffff0000, v1
	v_and_b32_e32 v143, 0xffff0000, v2
	v_lshlrev_b32_e32 v144, 16, v3
	v_and_b32_e32 v145, 0xffff0000, v3
	v_and_b32_e32 v146, 0xffff0000, v4
	v_lshlrev_b32_e32 v147, 16, v5
	v_and_b32_e32 v148, 0xffff0000, v5
	v_and_b32_e32 v149, 0xffff0000, v6
	v_lshlrev_b32_e32 v150, 16, v7
	v_and_b32_e32 v151, 0xffff0000, v7
	v_lshlrev_b32_e32 v152, 16, v0
	v_lshlrev_b32_e32 v153, 16, v4
	v_lshlrev_b32_e32 v154, 16, v2
	v_lshlrev_b32_e32 v155, 16, v6
	v_lshlrev_b32_e32 v126, 16, v13
	v_lshlrev_b32_e32 v130, 16, v12
	v_and_b32_e32 v127, 0xffff0000, v13
	v_and_b32_e32 v131, 0xffff0000, v12
	v_lshlrev_b32_e32 v124, 16, v9
	v_lshlrev_b32_e32 v128, 16, v8
	v_and_b32_e32 v125, 0xffff0000, v9
	v_and_b32_e32 v129, 0xffff0000, v8
	v_lshlrev_b32_e32 v116, 16, v15
	v_lshlrev_b32_e32 v122, 16, v14
	v_and_b32_e32 v117, 0xffff0000, v15
	v_and_b32_e32 v123, 0xffff0000, v14
	v_lshlrev_b32_e32 v118, 16, v11
	v_lshlrev_b32_e32 v120, 16, v10
	v_and_b32_e32 v119, 0xffff0000, v11
	v_and_b32_e32 v121, 0xffff0000, v10
	global_load_dwordx4 v[12:15], v[22:23], off
	global_load_dwordx4 v[8:11], v[16:17], off
	global_load_dwordx4 v[0:3], v[18:19], off
	global_load_dwordx4 v[4:7], v[20:21], off
	s_nop 0
	global_load_dwordx4 v[16:19], v[26:27], off
	global_load_dwordx4 v[20:23], v[24:25], off
	v_mbcnt_lo_u32_b32 v137, -1, 0
	v_mbcnt_hi_u32_b32 v137, -1, v137
	s_lshl_b64 s[0:1], s[0:1], 14
	v_add_u32_e32 v141, s33, v137
	v_ashrrev_i32_e32 v136, 7, v141
	s_add_u32 s0, s50, s0
	v_bfe_u32 v156, v137, 4, 2
	v_lshlrev_b32_e32 v114, 4, v136
	s_addc_u32 s1, s51, s1
	s_ashr_i32 s31, s30, 31
	v_ashrrev_i32_e32 v140, 6, v141
	v_and_b32_e32 v139, 15, v137
	v_lshlrev_b32_e32 v112, 4, v156
	v_mov_b32_e32 v113, v99
	v_ashrrev_i32_e32 v115, 31, v114
	s_lshl_b64 s[4:5], s[30:31], 7
	v_and_b32_e32 v138, 1, v140
	v_lshlrev_b32_e32 v98, 3, v156
	v_lshl_add_u64 v[24:25], s[0:1], 0, v[112:113]
	v_lshl_add_u64 v[28:29], v[114:115], 1, s[16:17]
	v_lshlrev_b32_e32 v49, 7, v139
	v_lshl_add_u64 v[26:27], v[24:25], 0, s[22:23]
	v_or_b32_e32 v113, s4, v139
	v_lshl_add_u64 v[104:105], v[28:29], 0, v[98:99]
	v_lshl_or_b32 v28, v138, 13, v49
	v_mov_b32_e32 v29, v99
	v_lshlrev_b32_e32 v115, 6, v138
	v_lshl_add_u64 v[30:31], v[24:25], 0, v[28:29]
	v_lshl_add_u64 v[28:29], v[26:27], 0, v[28:29]
	v_or_b32_e32 v132, v113, v115
	v_mov_b32_e32 v133, s5
	v_lshlrev_b32_e32 v48, 2, v138
	global_load_dwordx4 v[72:75], v[30:31], off
	global_load_dwordx4 v[36:39], v[30:31], off offset:64
	global_load_dwordx4 v[68:71], v[28:29], off
	global_load_dwordx4 v[44:47], v[28:29], off offset:64
	v_lshlrev_b64 v[28:29], 7, v[132:133]
	v_lshl_add_u64 v[28:29], v[104:105], 0, v[28:29]
	v_or_b32_e32 v50, 1, v48
	global_load_dwordx2 v[110:111], v[28:29], off
	v_lshl_or_b32 v28, v50, 11, v49
	v_mov_b32_e32 v29, v99
	v_lshl_add_u64 v[30:31], v[24:25], 0, v[28:29]
	v_lshl_add_u64 v[28:29], v[26:27], 0, v[28:29]
	v_lshl_or_b32 v132, v50, 4, v113
	global_load_dwordx4 v[92:95], v[30:31], off
	global_load_dwordx4 v[80:83], v[30:31], off offset:64
	global_load_dwordx4 v[88:91], v[28:29], off
	global_load_dwordx4 v[84:87], v[28:29], off offset:64
	v_lshlrev_b64 v[28:29], 7, v[132:133]
	v_lshl_add_u64 v[28:29], v[104:105], 0, v[28:29]
	v_or_b32_e32 v50, 2, v48
	global_load_dwordx2 v[108:109], v[28:29], off
	v_lshl_or_b32 v28, v50, 11, v49
	v_mov_b32_e32 v29, v99
	v_lshl_add_u64 v[30:31], v[24:25], 0, v[28:29]
	v_lshl_add_u64 v[28:29], v[26:27], 0, v[28:29]
	v_lshl_or_b32 v132, v50, 4, v113
	global_load_dwordx4 v[60:63], v[30:31], off
	global_load_dwordx4 v[56:59], v[30:31], off offset:64
	global_load_dwordx4 v[76:79], v[28:29], off
	global_load_dwordx4 v[64:67], v[28:29], off offset:64
	v_lshlrev_b64 v[28:29], 7, v[132:133]
	v_lshl_add_u64 v[28:29], v[104:105], 0, v[28:29]
	v_or_b32_e32 v132, 3, v48
	global_load_dwordx2 v[106:107], v[28:29], off
	v_lshl_or_b32 v28, v132, 11, v49
	v_lshl_or_b32 v132, v132, 4, v113
	v_mov_b32_e32 v29, v99
	v_lshlrev_b64 v[132:133], 7, v[132:133]
	v_lshl_add_u64 v[24:25], v[24:25], 0, v[28:29]
	v_lshl_add_u64 v[26:27], v[26:27], 0, v[28:29]
	v_lshl_add_u64 v[104:105], v[104:105], 0, v[132:133]
	global_load_dwordx4 v[52:55], v[24:25], off
	global_load_dwordx4 v[28:31], v[24:25], off offset:64
	global_load_dwordx4 v[48:51], v[26:27], off
	s_nop 0
	global_load_dwordx4 v[24:27], v[26:27], off offset:64
	s_mov_b64 s[40:41], -1
	global_load_dwordx2 v[104:105], v[104:105], off
	v_mbcnt_lo_u32_b32 v113, -1, 0
	v_mbcnt_hi_u32_b32 v113, -1, v113
	s_mov_b32 s31, 0
	v_add_u32_e32 v157, s33, v113
	v_lshlrev_b32_e32 v132, 3, v113
	v_ashrrev_i32_e32 v133, 3, v157
	v_and_b32_e32 v132, 56, v132
	v_mad_u64_u32 v[132:133], s[0:1], v133, s3, v[132:133]
	v_lshl_add_u32 v132, v132, 2, 16
	v_add_u32_e32 v133, 0x4104, v132
	ds_write2_b32 v132, v134, v135 offset0:1 offset1:2
	ds_write2_b32 v133, v146, v147 offset1:1
	v_add_u32_e32 v133, 0x410c, v132
	v_lshlrev_b32_e32 v113, 2, v113
	ds_write2_b32 v132, v142, v154 offset0:3 offset1:4
	ds_write2_b32 v133, v148, v155 offset1:1
	v_add_u32_e32 v133, 0x4114, v132
	ds_write2_b32 v132, v143, v144 offset0:5 offset1:6
	ds_write2_b32 v133, v149, v150 offset1:1
	ds_write2_b32 v132, v152, v145 offset1:7
	v_add_u32_e32 v132, 0x4000, v132
	v_and_b32_e32 v147, 0xfc, v113
	ds_write2_b32 v132, v153, v151 offset0:64 offset1:71
	v_ashrrev_i32_e32 v146, 6, v157
	v_add_u32_e32 v132, 16, v147
	v_mad_u64_u32 v[134:135], s[0:1], v146, s25, v[132:133]
	v_lshl_or_b32 v133, v146, 3, 1
	s_waitcnt lgkmcnt(0)
	s_barrier
; #define LBAR do { asm volatile("s_waitcnt lgkmcnt(0)" ::: "memory"); __builtin_amdgcn_s_barrier(); } while (0)
; __device__ __forceinline__ void gla_cumsum(const P& p, uint4 a, uint4 b, char* sm) {
;     ...
;   {
;     float* segF = (float*)(sm + G_SEG);
;     float* segB = segF + 8 * 64;
;     int dk = tid & 63, seg = tid >> 6;
;     float a = 0.f, c = 0.f;
; #pragma unroll
;     for (int i = 0; i < 8; ++i) { a += bF[(seg * 8 + i) * 65 + dk]; bF[(seg * 8 + i) * 65 + dk] = a; }
; #pragma unroll
;     for (int i = 7; i >= 0; --i) { c += bB[(seg * 8 + i) * 65 + dk]; bB[(seg * 8 + i) * 65 + dk] = c; }
;     segF[seg * 64 + dk] = a; segB[seg * 64 + dk] = c;
;     LBAR;
;     float offF = 0.f, offB = 0.f;
; #pragma unroll
;     for (int s2 = 0; s2 < 8; ++s2) {
;       float f = segF[s2 * 64 + dk], g = segB[s2 * 64 + dk];
;       offF += (s2 < seg) ? f : 0.f;
;       offB += (s2 > seg) ? g : 0.f;
;     }
; #pragma unroll
;     for (int i = 0; i < 8; ++i) { bF[(seg * 8 + i) * 65 + dk] += offF; bB[(seg * 8 + i) * 65 + dk] += offB; }
;   }
;   LBAR;
	ds_read_b32 v113, v134
	v_mad_u64_u32 v[132:133], s[0:1], v133, s27, v[132:133]
	ds_read2_b32 v[142:143], v132 offset1:65
	ds_read2_b32 v[144:145], v132 offset0:130 offset1:195
	s_waitcnt lgkmcnt(2)
	v_add_f32_e32 v113, 0, v113
	ds_write_b32 v134, v113
	v_add_u32_e32 v148, 0x400, v132
	s_waitcnt lgkmcnt(2)
	v_add_f32_e32 v113, v113, v142
	v_add_f32_e32 v133, v113, v143
	ds_write2_b32 v132, v113, v133 offset1:65
	s_waitcnt lgkmcnt(2)
	v_add_f32_e32 v113, v133, v144
	v_add_f32_e32 v133, v113, v145
	ds_write2_b32 v132, v113, v133 offset0:130 offset1:195
	ds_read2_b32 v[142:143], v148 offset0:4 offset1:69
	v_add_u32_e32 v149, 0x4400, v132
	v_add_u32_e32 v150, 0x4200, v132
	v_add_u32_e32 v151, 0x4000, v132
	v_cmp_lt_i32_e32 vcc, 0, v146
	s_waitcnt lgkmcnt(0)
	v_add_f32_e32 v113, v133, v142
	v_add_f32_e32 v133, v113, v143
	ds_write2_b32 v148, v113, v133 offset0:4 offset1:69
	ds_read_b32 v113, v132 offset:1560
	ds_read_b32 v135, v132 offset:18200
	v_or_b32_e32 v154, 0x500, v147
	v_add_u32_e32 v155, s84, v154
	v_add_u32_e32 v154, s42, v154
	s_waitcnt lgkmcnt(1)
	v_add_f32_e32 v133, v133, v113
	s_waitcnt lgkmcnt(0)
	v_add_f32_e32 v113, 0, v135
	ds_write_b32 v132, v133 offset:1560
	ds_write_b32 v132, v113 offset:18200
	ds_read2_b32 v[142:143], v149 offset0:68 offset1:133
	s_waitcnt lgkmcnt(0)
	v_add_f32_e32 v113, v113, v143
	v_add_f32_e32 v135, v113, v142
	ds_write2_b32 v149, v135, v113 offset0:68 offset1:133
	ds_read2_b32 v[142:143], v150 offset0:66 offset1:131
	ds_read2_b32 v[144:145], v151 offset0:64 offset1:129
	v_lshlrev_b32_e32 v113, 2, v156
	v_or_b32_e32 v156, 0x600, v147
	s_waitcnt lgkmcnt(1)
	v_add_f32_e32 v135, v135, v143
	ds_read_b32 v143, v134 offset:16640
	v_add_f32_e32 v142, v135, v142
	ds_write2_b32 v150, v142, v135 offset0:66 offset1:131
	s_waitcnt lgkmcnt(2)
	v_add_f32_e32 v135, v142, v145
	v_add_f32_e32 v142, v135, v144
	ds_write2_b32 v151, v142, v135 offset0:64 offset1:129
	s_waitcnt lgkmcnt(2)
	v_add_f32_e32 v135, v142, v143
	v_lshlrev_b32_e32 v142, 2, v157
	v_add_u32_e32 v143, s84, v142
	ds_write_b32 v134, v135 offset:16640
	ds_write_b32 v143, v133
	v_add_u32_e32 v133, s42, v142
	v_or_b32_e32 v142, 0x100, v147
	v_or_b32_e32 v144, 0x200, v147
	ds_write_b32 v133, v135
	v_add_u32_e32 v133, s84, v147
	v_add_u32_e32 v135, s42, v147
	v_add_u32_e32 v143, s84, v142
	v_add_u32_e32 v142, s42, v142
	v_add_u32_e32 v145, s84, v144
	v_add_u32_e32 v144, s42, v144
	s_waitcnt lgkmcnt(0)
	s_barrier
	ds_read_b32 v133, v133
	ds_read_b32 v135, v135
	ds_read_b32 v143, v143
	ds_read_b32 v142, v142
	ds_read_b32 v145, v145
	ds_read_b32 v144, v144
	ds_read_b32 v152, v132 offset:1560
	ds_read_b32 v153, v132 offset:18200
	s_waitcnt lgkmcnt(7)
	v_add_f32_e32 v133, 0, v133
	v_cndmask_b32_e32 v133, 0, v133, vcc
	s_waitcnt lgkmcnt(6)
	v_add_f32_e32 v135, 0, v135
	v_cmp_gt_i32_e32 vcc, 0, v146
	v_add_u32_e32 v157, s84, v156
	v_add_u32_e32 v156, s42, v156
	v_cndmask_b32_e32 v135, 0, v135, vcc
	v_cmp_lt_i32_e32 vcc, 1, v146
	s_waitcnt lgkmcnt(5)
	s_nop 0
	v_cndmask_b32_e32 v143, 0, v143, vcc
	v_cmp_gt_i32_e32 vcc, 1, v146
	v_add_f32_e32 v133, v133, v143
	s_waitcnt lgkmcnt(4)
	v_cndmask_b32_e32 v142, 0, v142, vcc
	v_cmp_lt_i32_e32 vcc, 2, v146
	v_add_f32_e32 v135, v135, v142
	s_waitcnt lgkmcnt(3)
	v_cndmask_b32_e32 v142, 0, v145, vcc
	v_cmp_gt_i32_e32 vcc, 2, v146
	v_add_f32_e32 v133, v133, v142
	s_waitcnt lgkmcnt(2)
	v_cndmask_b32_e32 v142, 0, v144, vcc
	v_add_f32_e32 v135, v135, v142
	v_or_b32_e32 v142, 0x300, v147
	v_or_b32_e32 v144, 0x400, v147
	v_add_u32_e32 v143, s84, v142
	v_add_u32_e32 v142, s42, v142
	v_add_u32_e32 v145, s84, v144
	v_add_u32_e32 v144, s42, v144
	ds_read_b32 v143, v143
	ds_read_b32 v142, v142
	ds_read_b32 v145, v145
	ds_read_b32 v144, v144
	ds_read_b32 v155, v155
	ds_read_b32 v154, v154
	ds_read_b32 v157, v157
	ds_read_b32 v156, v156
	v_cmp_lt_i32_e32 vcc, 3, v146
	s_waitcnt lgkmcnt(7)
	s_nop 0
	v_cndmask_b32_e32 v143, 0, v143, vcc
	v_cmp_gt_i32_e32 vcc, 3, v146
	v_add_f32_e32 v133, v133, v143
	v_or_b32_e32 v143, 0x700, v147
	s_waitcnt lgkmcnt(6)
	v_cndmask_b32_e32 v142, 0, v142, vcc
	v_cmp_lt_i32_e32 vcc, 4, v146
	v_add_f32_e32 v135, v135, v142
	s_waitcnt lgkmcnt(5)
	v_cndmask_b32_e32 v142, 0, v145, vcc
	v_cmp_gt_i32_e32 vcc, 4, v146
	v_add_f32_e32 v133, v133, v142
	s_waitcnt lgkmcnt(4)
	v_cndmask_b32_e32 v142, 0, v144, vcc
	v_cmp_lt_i32_e32 vcc, 5, v146
	v_add_f32_e32 v135, v135, v142
	v_add_u32_e32 v144, s84, v143
	s_waitcnt lgkmcnt(3)
	v_cndmask_b32_e32 v142, 0, v155, vcc
	v_cmp_gt_i32_e32 vcc, 5, v146
	v_add_f32_e32 v133, v133, v142
	ds_read_b32 v144, v144
	s_waitcnt lgkmcnt(3)
	v_cndmask_b32_e32 v142, 0, v154, vcc
	v_cmp_lt_i32_e32 vcc, 6, v146
	v_add_f32_e32 v135, v135, v142
	s_waitcnt lgkmcnt(2)
	v_cndmask_b32_e32 v142, 0, v157, vcc
	v_cmp_gt_i32_e32 vcc, 6, v146
	v_add_f32_e32 v133, v133, v142
	s_waitcnt lgkmcnt(1)
	v_cndmask_b32_e32 v142, 0, v156, vcc
	v_add_f32_e32 v135, v135, v142
	v_add_u32_e32 v142, s42, v143
	ds_read_b32 v145, v142
	v_cmp_lt_i32_e32 vcc, 7, v146
	s_waitcnt lgkmcnt(1)
	s_nop 0
	v_cndmask_b32_e32 v142, 0, v144, vcc
	v_add_f32_e32 v133, v133, v142
	ds_read2st64_b32 v[142:143], v134 offset1:65
	v_cmp_gt_i32_e32 vcc, 7, v146
	s_waitcnt lgkmcnt(1)
	s_nop 0
	v_cndmask_b32_e32 v144, 0, v145, vcc
	v_add_f32_e32 v154, v135, v144
	ds_read2_b32 v[144:145], v132 offset1:65
	ds_read2_b32 v[146:147], v151 offset0:64 offset1:129
	s_waitcnt lgkmcnt(2)
	v_add_f32_e32 v135, v133, v142
	v_add_f32_e32 v142, v154, v143
	ds_write2st64_b32 v134, v135, v142 offset1:65
	ds_read2_b32 v[134:135], v132 offset0:130 offset1:195
	ds_read2_b32 v[142:143], v150 offset0:66 offset1:131
	s_waitcnt lgkmcnt(4)
	v_add_f32_e32 v144, v133, v144
	v_add_f32_e32 v145, v133, v145
	s_waitcnt lgkmcnt(3)
	v_add_f32_e32 v146, v154, v146
	ds_write2_b32 v132, v144, v145 offset1:65
	v_add_f32_e32 v144, v154, v147
	ds_write2_b32 v151, v146, v144 offset0:64 offset1:129
	s_waitcnt lgkmcnt(3)
	v_add_f32_e32 v146, v133, v134
	v_add_f32_e32 v147, v133, v135
	ds_read2_b32 v[134:135], v148 offset0:4 offset1:69
	ds_read2_b32 v[144:145], v149 offset0:68 offset1:133
	s_waitcnt lgkmcnt(4)
	v_add_f32_e32 v142, v154, v142
	ds_write2_b32 v132, v146, v147 offset0:130 offset1:195
	v_add_f32_e32 v143, v154, v143
	s_waitcnt lgkmcnt(2)
	v_add_f32_e32 v134, v133, v134
	v_add_f32_e32 v135, v133, v135
	v_add_f32_e32 v133, v133, v152
	ds_write_b32 v132, v133 offset:1560
	v_add_f32_e32 v133, v154, v153
	ds_write_b32 v132, v133 offset:18200
	v_lshlrev_b32_e32 v132, 3, v137
	ds_write2_b32 v150, v142, v143 offset0:66 offset1:131
	s_waitcnt lgkmcnt(4)
	v_add_f32_e32 v142, v154, v144
	ds_write2_b32 v148, v134, v135 offset0:4 offset1:69
	v_add_f32_e32 v134, v154, v145
	v_ashrrev_i32_e32 v133, 3, v141
	v_and_b32_e32 v132, 56, v132
	ds_write2_b32 v149, v142, v134 offset0:68 offset1:133
	v_mad_u64_u32 v[134:135], s[0:1], v133, s3, v[132:133]
	v_lshl_add_u32 v150, v134, 2, 16
	v_add_u32_e32 v142, 0x4100, v150
	s_waitcnt lgkmcnt(0)
	s_barrier
; __device__ __forceinline__ float bf2f(u16 h) { return __uint_as_float(((unsigned)h) << 16); }
; #define LBAR do { asm volatile("s_waitcnt lgkmcnt(0)" ::: "memory"); __builtin_amdgcn_s_barrier(); } while (0)
; __device__ __forceinline__ void gla_out_unit(const P& p, int unit, const OutRaw& raw) {
;     ...
;   {
;     int s = tid >> 3, d0 = (tid & 7) * 8;
;     const u16* pq = (const u16*)&raw.q; const u16* pk = (const u16*)&raw.k;
;     u16 oqf[8], oqb[8], okf[8], okb[8];
; #pragma unroll
;     for (int e = 0; e < 8; ++e) {
;       float bf = bF[s * 65 + d0 + e], bb = bB[s * 65 + d0 + e];
;       float qq = bf2f(pq[e]), kk = bf2f(pk[e]);
;       oqf[e] = f2bf(qq * __expf(bf)); oqb[e] = f2bf(qq * __expf(bb));
;       okf[e] = f2bf(kk * __expf(-bf)); okb[e] = f2bf(kk * __expf(-bb));
;     }
;     *(uint4*)(qf + s * LP + d0) = *(const uint4*)oqf;
;     *(uint4*)(qb + s * LP + d0) = *(const uint4*)oqb;
;     *(uint4*)(kf + s * LP + d0) = *(const uint4*)okf;
;     *(uint4*)(kb + s * LP + d0) = *(const uint4*)okb;
;     *(uint4*)(vT + (tid >> 3) * LP + (tid & 7) * 8) = raw.v0;
;     *(uint4*)(vT + ((tid + 512) >> 3) * LP + (tid & 7) * 8) = raw.v1;
;   }
;   LBAR;
;   int fr = lane & 15, fq = lane >> 4;
; #pragma unroll 1
;   for (int tI = 0; tI < 2; ++tI) {
;     int tile = wid * 2 + tI; int tt = tile >> 2, st = tile & 3;
	ds_read2_b32 v[134:135], v150 offset1:1
	ds_read2_b32 v[142:143], v142 offset1:1
	ds_read2_b32 v[144:145], v150 offset0:2 offset1:3
	ds_read2_b32 v[146:147], v150 offset0:4 offset1:5
	ds_read2_b32 v[148:149], v150 offset0:6 offset1:7
	v_add_u32_e32 v151, 0x4108, v150
	s_waitcnt lgkmcnt(3)
	v_mul_f32_e32 v157, 0x3fb8aa3b, v142
	v_mul_f32_e32 v142, 0xbfb8aa3b, v142
	v_exp_f32_e32 v157, v157
	v_exp_f32_e32 v142, v142
	v_add_u32_e32 v152, 0x4110, v150
	v_add_u32_e32 v154, 0x4118, v150
	ds_read2_b32 v[150:151], v151 offset1:1
	ds_read2_b32 v[152:153], v152 offset1:1
	ds_read2_b32 v[154:155], v154 offset1:1
	v_mul_f32_e32 v158, v157, v130
	v_mul_f32_e32 v159, v142, v128
	v_mul_f32_e32 v142, 0x3fb8aa3b, v135
	v_mul_f32_e32 v157, 0x3fb8aa3b, v143
	v_exp_f32_e32 v160, v157
	v_exp_f32_e32 v157, v142
	v_mul_f32_e32 v142, 0xbfb8aa3b, v143
	s_waitcnt lgkmcnt(2)
	v_mul_f32_e32 v143, 0x3fb8aa3b, v150
	v_exp_f32_e32 v143, v143
	v_exp_f32_e32 v142, v142
	v_mul_f32_e32 v156, 0x3fb8aa3b, v134
	v_mul_f32_e32 v134, 0xbfb8aa3b, v134
	v_mul_f32_e32 v162, v143, v126
	v_mul_f32_e32 v143, 0xbfb8aa3b, v144
	v_mul_f32_e32 v135, 0xbfb8aa3b, v135
	v_mul_f32_e32 v161, v142, v129
	v_mul_f32_e32 v142, 0x3fb8aa3b, v144
	v_mul_f32_e32 v150, 0xbfb8aa3b, v150
	v_exp_f32_e32 v144, v143
	v_mul_f32_e32 v143, 0x3fb8aa3b, v145
	v_mul_f32_e32 v163, 0x3fb8aa3b, v151
	v_mul_f32_e32 v145, 0xbfb8aa3b, v145
	v_exp_f32_e32 v156, v156
	v_exp_f32_e32 v134, v134
	v_exp_f32_e32 v135, v135
	v_exp_f32_e32 v142, v142
	v_exp_f32_e32 v150, v150
	v_exp_f32_e32 v143, v143
	v_exp_f32_e32 v163, v163
	v_exp_f32_e32 v145, v145
	v_mul_f32_e32 v160, v160, v131
	v_mul_f32_e32 v150, v150, v124
	v_pk_mul_f32 v[142:143], v[142:143], v[126:127]
	v_pk_mul_f32 v[130:131], v[156:157], v[130:131]
	v_mul_f32_e32 v156, v163, v127
	v_pk_mul_f32 v[126:127], v[144:145], v[124:125]
	v_mul_f32_e32 v124, 0xbfb8aa3b, v151
	v_pk_mul_f32 v[128:129], v[134:135], v[128:129]
	s_waitcnt lgkmcnt(1)
	v_mul_f32_e32 v134, 0x3fb8aa3b, v152
	v_exp_f32_e32 v124, v124
	v_exp_f32_e32 v134, v134
	s_waitcnt lgkmcnt(0)
	v_mul_f32_e32 v145, 0x3fb8aa3b, v154
	v_exp_f32_e32 v145, v145
	v_mul_f32_e32 v151, v124, v125
	v_mul_f32_e32 v157, v134, v122
	v_mul_f32_e32 v125, 0xbfb8aa3b, v146
	v_mul_f32_e32 v134, 0xbfb8aa3b, v152
	v_exp_f32_e32 v135, v134
	v_exp_f32_e32 v134, v125
	v_mul_f32_e32 v125, 0x3fb8aa3b, v153
	v_exp_f32_e32 v144, v125
	v_mul_f32_e32 v124, 0x3fb8aa3b, v146
	v_mul_f32_e32 v125, 0x3fb8aa3b, v147
	v_mul_f32_e32 v164, v145, v116
	v_mul_f32_e32 v163, v144, v123
	v_mul_f32_e32 v144, 0xbfb8aa3b, v153
	v_exp_f32_e32 v144, v144
	v_mul_f32_e32 v145, 0xbfb8aa3b, v154
	v_exp_f32_e32 v124, v124
	v_mul_f32_e32 v152, v135, v120
	v_exp_f32_e32 v125, v125
	v_mul_f32_e32 v135, 0xbfb8aa3b, v147
	v_mul_f32_e32 v153, v144, v121
	v_mul_f32_e32 v144, 0x3fb8aa3b, v148
	v_exp_f32_e32 v147, v145
	v_mul_f32_e32 v145, 0x3fb8aa3b, v149
	v_exp_f32_e32 v144, v144
	v_exp_f32_e32 v145, v145
	v_pk_mul_f32 v[122:123], v[124:125], v[122:123]
	v_mul_f32_e32 v124, 0xbfb8aa3b, v149
	v_mul_f32_e32 v146, 0xbfb8aa3b, v148
	v_mul_f32_e32 v148, v147, v118
	v_pk_mul_f32 v[144:145], v[144:145], v[116:117]
	v_mul_f32_e32 v116, 0x3fb8aa3b, v155
	v_exp_f32_e32 v147, v124
	v_mul_f32_e32 v124, 0xbfb8aa3b, v155
	v_exp_f32_e32 v135, v135
	v_exp_f32_e32 v146, v146
	v_exp_f32_e32 v116, v116
	v_exp_f32_e32 v149, v124
	v_mul_lo_u32 v133, v133, s44
	v_lshlrev_b32_e32 v132, 1, v132
	v_mul_f32_e32 v154, v116, v117
	v_pk_mul_f32 v[124:125], v[146:147], v[118:119]
	v_pk_mul_f32 v[120:121], v[134:135], v[120:121]
	v_mul_f32_e32 v134, v149, v119
	v_add3_u32 v135, 16, v133, v132
	v_cvt_pk_bf16_f32 v119, v144, v145
	v_cvt_pk_bf16_f32 v118, v122, v123
	v_cvt_pk_bf16_f32 v117, v142, v143
	v_cvt_pk_bf16_f32 v116, v130, v131
	ds_write_b128 v135, v[116:119] offset:33280
	v_cvt_pk_bf16_f32 v119, v164, v154
	v_cvt_pk_bf16_f32 v118, v157, v163
	v_cvt_pk_bf16_f32 v117, v162, v156
	v_cvt_pk_bf16_f32 v116, v158, v160
	ds_write_b128 v135, v[116:119] offset:42496
	v_cvt_pk_bf16_f32 v119, v124, v125
	v_cvt_pk_bf16_f32 v118, v120, v121
	v_cvt_pk_bf16_f32 v117, v126, v127
	v_cvt_pk_bf16_f32 v116, v128, v129
	ds_write_b128 v135, v[116:119] offset:51712
	v_cvt_pk_bf16_f32 v119, v148, v134
	v_cvt_pk_bf16_f32 v118, v152, v153
	v_cvt_pk_bf16_f32 v117, v150, v151
	v_cvt_pk_bf16_f32 v116, v159, v161
	ds_write_b128 v135, v[116:119] offset:60928
	v_add3_u32 v116, s45, v133, v132
	ds_write_b128 v116, v[40:43]
	v_add_u32_e32 v40, 0x200, v141
	v_lshrrev_b32_e32 v40, 3, v40
	v_mul_lo_u32 v40, v40, s44
	v_add3_u32 v40, s45, v40, v132
	ds_write_b128 v40, v[32:35]
	s_waitcnt lgkmcnt(0)
	v_or_b32_e32 v32, v114, v139
	v_lshlrev_b32_e32 v40, 5, v140
	v_mul_lo_u32 v33, v32, s46
	v_add_u32_e32 v34, 16, v112
	v_or_b32_e32 v117, v114, v113
	v_lshl_add_u32 v32, v33, 1, v34
	v_mul_lo_u32 v35, v117, s44
	v_or_b32_e32 v116, 1, v117
	v_or_b32_e32 v118, 2, v117
	v_or_b32_e32 v114, 3, v117
	v_and_or_b32 v40, v40, 32, v139
	s_barrier
